# P6: half-workgroup 0 starts its epilogue during half 1's last MMA phase (align barrier moved behind the epilogue, half 1's last K-loop barrier deferred); on top of the peeled first iterations
# baseline (speedup 1.0000x reference)
.LBB0_664:
	ds_read_b128 v[142:145], v155
	ds_read_b128 v[160:163], v155 offset:1024
	ds_read_b128 v[166:169], v155 offset:2048
	ds_read_b128 v[170:173], v155 offset:3072
	ds_read_b128 v[174:177], v156
	ds_read_b128 v[178:181], v156 offset:1024
	ds_read_b128 v[182:185], v156 offset:2048
	ds_read_b128 v[186:189], v156 offset:3072
	s_add_u32 vcc_lo, s14, 0x100
	s_addc_u32 vcc_hi, s15, 0
	s_cmp_eq_u32 s86, 12
	s_cselect_b32 s24, s78, vcc_lo
	s_cselect_b32 s25, s13, vcc_hi
	s_cselect_b32 s22, s79, s80
	s_cselect_b32 s23, s11, s81
	s_add_u32 s20, s24, 0x80
	s_addc_u32 s21, s25, 0
	ds_read_b128 v[190:193], v157
	ds_read_b128 v[194:197], v157 offset:1024
	ds_read_b128 v[198:201], v157 offset:2048
	ds_read_b128 v[202:205], v157 offset:3072
	ds_read_b128 v[206:209], v157 offset:4096
	ds_read_b128 v[210:213], v157 offset:5120
	ds_read_b128 v[214:217], v157 offset:6144
	ds_read_b128 v[218:221], v157 offset:7168
	s_add_u32 s14, s14, 0x40080
	s_addc_u32 s15, s15, 0
	s_mov_b32 s87, m0
	s_mov_b32 m0, s82
	s_nop 0
	global_load_lds_dwordx4 v150, s[14:15]
	s_mov_b32 m0, s87
	s_add_i32 s87, s30, 0xe000
	s_mov_b32 s90, m0
	s_mov_b32 m0, s87
	s_nop 0
	global_load_lds_dwordx4 v152, s[14:15]
	s_mov_b32 m0, s90
	s_waitcnt vmcnt(8)
	s_waitcnt lgkmcnt(0)
	s_barrier
	s_setprio 1
	s_waitcnt lgkmcnt(7)
	v_mfma_f32_16x16x32_bf16 v[124:127], v[142:145], v[190:193], v[124:127]
	v_mfma_f32_16x16x32_bf16 v[120:123], v[166:169], v[190:193], v[120:123]
	s_waitcnt lgkmcnt(5)
	v_mfma_f32_16x16x32_bf16 v[108:111], v[142:145], v[198:201], v[108:111]
	v_mfma_f32_16x16x32_bf16 v[104:107], v[166:169], v[198:201], v[104:107]
	s_waitcnt lgkmcnt(3)
	v_mfma_f32_16x16x32_bf16 v[92:95], v[142:145], v[206:209], v[92:95]
	v_mfma_f32_16x16x32_bf16 v[88:91], v[166:169], v[206:209], v[88:91]
	s_waitcnt lgkmcnt(1)
	v_mfma_f32_16x16x32_bf16 v[76:79], v[142:145], v[214:217], v[76:79]
	v_mfma_f32_16x16x32_bf16 v[72:75], v[166:169], v[214:217], v[72:75]
	v_mfma_f32_16x16x32_bf16 v[124:127], v[160:163], v[194:197], v[124:127]
	v_mfma_f32_16x16x32_bf16 v[120:123], v[170:173], v[194:197], v[120:123]
	v_mfma_f32_16x16x32_bf16 v[108:111], v[160:163], v[202:205], v[108:111]
	v_mfma_f32_16x16x32_bf16 v[104:107], v[170:173], v[202:205], v[104:107]
	v_mfma_f32_16x16x32_bf16 v[92:95], v[160:163], v[210:213], v[92:95]
	v_mfma_f32_16x16x32_bf16 v[88:91], v[170:173], v[210:213], v[88:91]
	s_waitcnt lgkmcnt(0)
	v_mfma_f32_16x16x32_bf16 v[76:79], v[160:163], v[218:221], v[76:79]
	v_mfma_f32_16x16x32_bf16 v[72:75], v[170:173], v[218:221], v[72:75]
	s_setprio 0
	s_setprio 1
	v_mfma_f32_16x16x32_bf16 v[116:119], v[174:177], v[190:193], v[116:119]
	v_mfma_f32_16x16x32_bf16 v[112:115], v[182:185], v[190:193], v[112:115]
	v_mfma_f32_16x16x32_bf16 v[100:103], v[174:177], v[198:201], v[100:103]
	v_mfma_f32_16x16x32_bf16 v[96:99], v[182:185], v[198:201], v[96:99]
	v_mfma_f32_16x16x32_bf16 v[84:87], v[174:177], v[206:209], v[84:87]
	v_mfma_f32_16x16x32_bf16 v[80:83], v[182:185], v[206:209], v[80:83]
	v_mfma_f32_16x16x32_bf16 v[68:71], v[174:177], v[214:217], v[68:71]
	v_mfma_f32_16x16x32_bf16 v[64:67], v[182:185], v[214:217], v[64:67]
	v_mfma_f32_16x16x32_bf16 v[116:119], v[178:181], v[194:197], v[116:119]
	v_mfma_f32_16x16x32_bf16 v[112:115], v[186:189], v[194:197], v[112:115]
	v_mfma_f32_16x16x32_bf16 v[100:103], v[178:181], v[202:205], v[100:103]
	v_mfma_f32_16x16x32_bf16 v[96:99], v[186:189], v[202:205], v[96:99]
	v_mfma_f32_16x16x32_bf16 v[84:87], v[178:181], v[210:213], v[84:87]
	v_mfma_f32_16x16x32_bf16 v[80:83], v[186:189], v[210:213], v[80:83]
	v_mfma_f32_16x16x32_bf16 v[68:71], v[178:181], v[218:221], v[68:71]
	v_mfma_f32_16x16x32_bf16 v[64:67], v[186:189], v[218:221], v[64:67]
	s_setprio 0
	s_barrier
	ds_read_b128 v[190:193], v157 offset:16384
	ds_read_b128 v[194:197], v157 offset:17408
	ds_read_b128 v[198:201], v157 offset:18432
	ds_read_b128 v[202:205], v157 offset:19456
	ds_read_b128 v[206:209], v157 offset:20480
	ds_read_b128 v[210:213], v157 offset:21504
	ds_read_b128 v[214:217], v157 offset:22528
	ds_read_b128 v[218:221], v157 offset:23552
	s_mov_b32 s14, m0
	s_mov_b32 m0, s31
	s_nop 0
	global_load_lds_dwordx4 v151, s[22:23]
	s_mov_b32 m0, s14
	s_nop 0
	s_mov_b32 s14, m0
	s_mov_b32 m0, s34
	s_nop 0
	global_load_lds_dwordx4 v153, s[22:23]
	s_mov_b32 m0, s14
	s_add_u32 s14, s22, 0x40000
	s_addc_u32 s15, s23, 0
	s_mov_b32 s87, m0
	s_mov_b32 m0, s35
	s_nop 0
	global_load_lds_dwordx4 v151, s[14:15]
	s_mov_b32 m0, s87
	s_nop 0
	s_mov_b32 s87, m0
	s_mov_b32 m0, s38
	s_nop 0
	global_load_lds_dwordx4 v153, s[14:15]
	s_mov_b32 m0, s87
	s_mov_b32 s14, m0
	s_mov_b32 m0, s30
	s_nop 0
	global_load_lds_dwordx4 v150, s[24:25]
	s_mov_b32 m0, s14
	s_nop 0
	s_mov_b32 s14, m0
	s_mov_b32 m0, s39
	s_nop 0
	global_load_lds_dwordx4 v152, s[24:25]
	s_mov_b32 m0, s14
	s_waitcnt vmcnt(8)
	s_waitcnt lgkmcnt(0)
	s_barrier
	s_setprio 1
	s_waitcnt lgkmcnt(7)
	v_mfma_f32_16x16x32_bf16 v[60:63], v[142:145], v[190:193], v[60:63]
	v_mfma_f32_16x16x32_bf16 v[56:59], v[166:169], v[190:193], v[56:59]
	s_waitcnt lgkmcnt(5)
	v_mfma_f32_16x16x32_bf16 v[44:47], v[142:145], v[198:201], v[44:47]
	v_mfma_f32_16x16x32_bf16 v[40:43], v[166:169], v[198:201], v[40:43]
	s_waitcnt lgkmcnt(3)
	v_mfma_f32_16x16x32_bf16 v[28:31], v[142:145], v[206:209], v[28:31]
	v_mfma_f32_16x16x32_bf16 v[24:27], v[166:169], v[206:209], v[24:27]
	s_waitcnt lgkmcnt(1)
	v_mfma_f32_16x16x32_bf16 v[12:15], v[142:145], v[214:217], v[12:15]
	v_mfma_f32_16x16x32_bf16 v[8:11], v[166:169], v[214:217], v[8:11]
	v_mfma_f32_16x16x32_bf16 v[60:63], v[160:163], v[194:197], v[60:63]
	v_mfma_f32_16x16x32_bf16 v[56:59], v[170:173], v[194:197], v[56:59]
	v_mfma_f32_16x16x32_bf16 v[44:47], v[160:163], v[202:205], v[44:47]
	v_mfma_f32_16x16x32_bf16 v[40:43], v[170:173], v[202:205], v[40:43]
	v_mfma_f32_16x16x32_bf16 v[28:31], v[160:163], v[210:213], v[28:31]
	v_mfma_f32_16x16x32_bf16 v[24:27], v[170:173], v[210:213], v[24:27]
	s_waitcnt lgkmcnt(0)
	v_mfma_f32_16x16x32_bf16 v[12:15], v[160:163], v[218:221], v[12:15]
	v_mfma_f32_16x16x32_bf16 v[8:11], v[170:173], v[218:221], v[8:11]
	s_setprio 0
	s_setprio 1
	v_mfma_f32_16x16x32_bf16 v[52:55], v[174:177], v[190:193], v[52:55]
	v_mfma_f32_16x16x32_bf16 v[48:51], v[182:185], v[190:193], v[48:51]
	v_mfma_f32_16x16x32_bf16 v[36:39], v[174:177], v[198:201], v[36:39]
	v_mfma_f32_16x16x32_bf16 v[32:35], v[182:185], v[198:201], v[32:35]
	v_mfma_f32_16x16x32_bf16 v[20:23], v[174:177], v[206:209], v[20:23]
	v_mfma_f32_16x16x32_bf16 v[16:19], v[182:185], v[206:209], v[16:19]
	v_mfma_f32_16x16x32_bf16 v[4:7], v[174:177], v[214:217], v[4:7]
	v_mfma_f32_16x16x32_bf16 v[0:3], v[182:185], v[214:217], v[0:3]
	v_mfma_f32_16x16x32_bf16 v[52:55], v[178:181], v[194:197], v[52:55]
	v_mfma_f32_16x16x32_bf16 v[48:51], v[186:189], v[194:197], v[48:51]
	v_mfma_f32_16x16x32_bf16 v[36:39], v[178:181], v[202:205], v[36:39]
	v_mfma_f32_16x16x32_bf16 v[32:35], v[186:189], v[202:205], v[32:35]
	v_mfma_f32_16x16x32_bf16 v[20:23], v[178:181], v[210:213], v[20:23]
	v_mfma_f32_16x16x32_bf16 v[16:19], v[186:189], v[210:213], v[16:19]
	v_mfma_f32_16x16x32_bf16 v[4:7], v[178:181], v[218:221], v[4:7]
	v_mfma_f32_16x16x32_bf16 v[0:3], v[186:189], v[218:221], v[0:3]
	s_setprio 0
	s_barrier
	ds_read_b128 v[142:145], v158
	ds_read_b128 v[160:163], v158 offset:1024
	ds_read_b128 v[166:169], v158 offset:2048
	ds_read_b128 v[170:173], v158 offset:3072
	ds_read_b128 v[174:177], v159
	ds_read_b128 v[178:181], v159 offset:1024
	ds_read_b128 v[182:185], v159 offset:2048
	ds_read_b128 v[186:189], v159 offset:3072
	ds_read_b128 v[190:193], v157 offset:32768
	ds_read_b128 v[194:197], v157 offset:33792
	ds_read_b128 v[198:201], v157 offset:34816
	ds_read_b128 v[202:205], v157 offset:35840
	ds_read_b128 v[206:209], v157 offset:36864
	ds_read_b128 v[210:213], v157 offset:37888
	ds_read_b128 v[214:217], v157 offset:38912
	ds_read_b128 v[218:221], v157 offset:39936
	s_add_u32 s14, s24, 0x40000
	s_addc_u32 s15, s25, 0
	s_mov_b32 s24, m0
	s_mov_b32 m0, s40
	s_nop 0
	global_load_lds_dwordx4 v150, s[14:15]
	s_mov_b32 m0, s24
	s_nop 0
	s_mov_b32 s24, m0
	s_mov_b32 m0, s41
	s_nop 0
	global_load_lds_dwordx4 v152, s[14:15]
	s_mov_b32 m0, s24
	s_waitcnt vmcnt(8)
	s_waitcnt lgkmcnt(0)
	s_barrier
	s_setprio 1
	s_waitcnt lgkmcnt(7)
	v_mfma_f32_16x16x32_bf16 v[124:127], v[142:145], v[190:193], v[124:127]
	v_mfma_f32_16x16x32_bf16 v[120:123], v[166:169], v[190:193], v[120:123]
	s_waitcnt lgkmcnt(5)
	v_mfma_f32_16x16x32_bf16 v[108:111], v[142:145], v[198:201], v[108:111]
	v_mfma_f32_16x16x32_bf16 v[104:107], v[166:169], v[198:201], v[104:107]
	s_waitcnt lgkmcnt(3)
	v_mfma_f32_16x16x32_bf16 v[92:95], v[142:145], v[206:209], v[92:95]
	v_mfma_f32_16x16x32_bf16 v[88:91], v[166:169], v[206:209], v[88:91]
	s_waitcnt lgkmcnt(1)
	v_mfma_f32_16x16x32_bf16 v[76:79], v[142:145], v[214:217], v[76:79]
	v_mfma_f32_16x16x32_bf16 v[72:75], v[166:169], v[214:217], v[72:75]
	v_mfma_f32_16x16x32_bf16 v[124:127], v[160:163], v[194:197], v[124:127]
	v_mfma_f32_16x16x32_bf16 v[120:123], v[170:173], v[194:197], v[120:123]
	v_mfma_f32_16x16x32_bf16 v[108:111], v[160:163], v[202:205], v[108:111]
	v_mfma_f32_16x16x32_bf16 v[104:107], v[170:173], v[202:205], v[104:107]
	v_mfma_f32_16x16x32_bf16 v[92:95], v[160:163], v[210:213], v[92:95]
	v_mfma_f32_16x16x32_bf16 v[88:91], v[170:173], v[210:213], v[88:91]
	s_waitcnt lgkmcnt(0)
	v_mfma_f32_16x16x32_bf16 v[76:79], v[160:163], v[218:221], v[76:79]
	v_mfma_f32_16x16x32_bf16 v[72:75], v[170:173], v[218:221], v[72:75]
	s_setprio 0
	s_setprio 1
	v_mfma_f32_16x16x32_bf16 v[116:119], v[174:177], v[190:193], v[116:119]
	v_mfma_f32_16x16x32_bf16 v[112:115], v[182:185], v[190:193], v[112:115]
	v_mfma_f32_16x16x32_bf16 v[100:103], v[174:177], v[198:201], v[100:103]
	v_mfma_f32_16x16x32_bf16 v[96:99], v[182:185], v[198:201], v[96:99]
	v_mfma_f32_16x16x32_bf16 v[84:87], v[174:177], v[206:209], v[84:87]
	v_mfma_f32_16x16x32_bf16 v[80:83], v[182:185], v[206:209], v[80:83]
	v_mfma_f32_16x16x32_bf16 v[68:71], v[174:177], v[214:217], v[68:71]
	v_mfma_f32_16x16x32_bf16 v[64:67], v[182:185], v[214:217], v[64:67]
	v_mfma_f32_16x16x32_bf16 v[116:119], v[178:181], v[194:197], v[116:119]
	v_mfma_f32_16x16x32_bf16 v[112:115], v[186:189], v[194:197], v[112:115]
	v_mfma_f32_16x16x32_bf16 v[100:103], v[178:181], v[202:205], v[100:103]
	v_mfma_f32_16x16x32_bf16 v[96:99], v[186:189], v[202:205], v[96:99]
	v_mfma_f32_16x16x32_bf16 v[84:87], v[178:181], v[210:213], v[84:87]
	v_mfma_f32_16x16x32_bf16 v[80:83], v[186:189], v[210:213], v[80:83]
	v_mfma_f32_16x16x32_bf16 v[68:71], v[178:181], v[218:221], v[68:71]
	v_mfma_f32_16x16x32_bf16 v[64:67], v[186:189], v[218:221], v[64:67]
	s_setprio 0
	s_barrier
	ds_read_b128 v[190:193], v157 offset:49152
	ds_read_b128 v[194:197], v157 offset:50176
	ds_read_b128 v[198:201], v157 offset:51200
	ds_read_b128 v[202:205], v157 offset:52224
	ds_read_b128 v[206:209], v157 offset:53248
	ds_read_b128 v[210:213], v157 offset:54272
	ds_read_b128 v[214:217], v157 offset:55296
	ds_read_b128 v[218:221], v157 offset:56320
	s_add_u32 s14, s22, 0x80
	s_addc_u32 s15, s23, 0
	s_mov_b32 s24, m0
	s_mov_b32 m0, s44
	s_nop 0
	global_load_lds_dwordx4 v151, s[14:15]
	s_mov_b32 m0, s24
	s_nop 0
	s_mov_b32 s24, m0
	s_mov_b32 m0, s45
	s_nop 0
	global_load_lds_dwordx4 v153, s[14:15]
	s_mov_b32 m0, s24
	s_add_u32 s14, s22, 0x40080
	s_addc_u32 s15, s23, 0
	s_mov_b32 s22, m0
	s_mov_b32 m0, s66
	s_nop 0
	global_load_lds_dwordx4 v151, s[14:15]
	s_mov_b32 m0, s22
	s_nop 0
	s_mov_b32 s22, m0
	s_mov_b32 m0, s67
	s_nop 0
	global_load_lds_dwordx4 v153, s[14:15]
	s_mov_b32 m0, s22
	s_mov_b32 s14, m0
	s_mov_b32 m0, s64
	s_nop 0
	global_load_lds_dwordx4 v150, s[20:21]
	s_mov_b32 m0, s14
	s_nop 0
	s_mov_b32 s14, m0
	s_mov_b32 m0, s65
	s_nop 0
	global_load_lds_dwordx4 v152, s[20:21]
	s_mov_b32 m0, s14
	s_waitcnt vmcnt(8)
	s_waitcnt lgkmcnt(0)
	s_barrier
	s_setprio 1
	s_waitcnt lgkmcnt(7)
	v_mfma_f32_16x16x32_bf16 v[60:63], v[142:145], v[190:193], v[60:63]
	v_mfma_f32_16x16x32_bf16 v[56:59], v[166:169], v[190:193], v[56:59]
	s_waitcnt lgkmcnt(5)
	v_mfma_f32_16x16x32_bf16 v[44:47], v[142:145], v[198:201], v[44:47]
	v_mfma_f32_16x16x32_bf16 v[40:43], v[166:169], v[198:201], v[40:43]
	s_waitcnt lgkmcnt(3)
	v_mfma_f32_16x16x32_bf16 v[28:31], v[142:145], v[206:209], v[28:31]
	v_mfma_f32_16x16x32_bf16 v[24:27], v[166:169], v[206:209], v[24:27]
	s_waitcnt lgkmcnt(1)
	v_mfma_f32_16x16x32_bf16 v[12:15], v[142:145], v[214:217], v[12:15]
	v_mfma_f32_16x16x32_bf16 v[8:11], v[166:169], v[214:217], v[8:11]
	v_mfma_f32_16x16x32_bf16 v[60:63], v[160:163], v[194:197], v[60:63]
	v_mfma_f32_16x16x32_bf16 v[56:59], v[170:173], v[194:197], v[56:59]
	v_mfma_f32_16x16x32_bf16 v[44:47], v[160:163], v[202:205], v[44:47]
	v_mfma_f32_16x16x32_bf16 v[40:43], v[170:173], v[202:205], v[40:43]
	v_mfma_f32_16x16x32_bf16 v[28:31], v[160:163], v[210:213], v[28:31]
	v_mfma_f32_16x16x32_bf16 v[24:27], v[170:173], v[210:213], v[24:27]
	s_waitcnt lgkmcnt(0)
	v_mfma_f32_16x16x32_bf16 v[12:15], v[160:163], v[218:221], v[12:15]
	v_mfma_f32_16x16x32_bf16 v[8:11], v[170:173], v[218:221], v[8:11]
	s_setprio 0
	s_setprio 1
	v_mfma_f32_16x16x32_bf16 v[52:55], v[174:177], v[190:193], v[52:55]
	v_mfma_f32_16x16x32_bf16 v[48:51], v[182:185], v[190:193], v[48:51]
	v_mfma_f32_16x16x32_bf16 v[36:39], v[174:177], v[198:201], v[36:39]
	v_mfma_f32_16x16x32_bf16 v[32:35], v[182:185], v[198:201], v[32:35]
	v_mfma_f32_16x16x32_bf16 v[20:23], v[174:177], v[206:209], v[20:23]
	v_mfma_f32_16x16x32_bf16 v[16:19], v[182:185], v[206:209], v[16:19]
	v_mfma_f32_16x16x32_bf16 v[4:7], v[174:177], v[214:217], v[4:7]
	v_mfma_f32_16x16x32_bf16 v[0:3], v[182:185], v[214:217], v[0:3]
	v_mfma_f32_16x16x32_bf16 v[52:55], v[178:181], v[194:197], v[52:55]
	v_mfma_f32_16x16x32_bf16 v[48:51], v[186:189], v[194:197], v[48:51]
	v_mfma_f32_16x16x32_bf16 v[36:39], v[178:181], v[202:205], v[36:39]
	v_mfma_f32_16x16x32_bf16 v[32:35], v[186:189], v[202:205], v[32:35]
	v_mfma_f32_16x16x32_bf16 v[20:23], v[178:181], v[210:213], v[20:23]
	v_mfma_f32_16x16x32_bf16 v[16:19], v[186:189], v[210:213], v[16:19]
	v_mfma_f32_16x16x32_bf16 v[4:7], v[178:181], v[218:221], v[4:7]
	v_mfma_f32_16x16x32_bf16 v[0:3], v[186:189], v[218:221], v[0:3]
	s_setprio 0
	s_cmp_lg_u32 s86, 12
	s_cbranch_scc1 .Lov6_bar
	s_cmp_eq_u64 s[8:9], 0
	s_cbranch_scc1 .Lov6_nobar

.Lov6_nobar:
	s_add_i32 s86, s86, 2
	s_add_u32 s80, s80, 0x100
	s_addc_u32 s81, s81, 0
	s_cmp_gt_u32 s86, 13
	s_mov_b64 s[14:15], vcc
	s_cbranch_scc0 .LBB0_664
	s_and_b64 vcc, exec, s[8:9]
.LBB0_667:
	v_lshl_add_u32 v146, s77, 8, v154
	v_ashrrev_i32_e32 v147, 31, v146
	v_lshl_add_u64 v[144:145], v[146:147], 2, s[6:7]
	global_load_dword v160, v[144:145], off
	v_lshlrev_b64 v[142:143], 13, v[146:147]
	s_lshl_b32 s14, s76, 8
	s_ashr_i32 s15, s14, 31
	s_lshl_b64 s[14:15], s[14:15], 1
	v_lshl_add_u64 v[142:143], s[48:49], 0, v[142:143]
	v_lshl_add_u64 v[142:143], v[142:143], 0, s[14:15]
	v_lshl_add_u64 v[142:143], v[142:143], 0, v[132:133]
	s_mov_b32 s11, 0x100000
	s_waitcnt vmcnt(0)
	v_fmamk_f32 v147, v160, 0x3a800000, v148
	v_rsq_f32_e32 v160, v147
	s_nop 0
	v_pk_mul_f32 v[126:127], v[126:127], v[160:161] op_sel_hi:[1,0]
	v_pk_mul_f32 v[124:125], v[124:125], v[160:161] op_sel_hi:[1,0]
	v_pk_mul_f32 v[122:123], v[122:123], v[160:161] op_sel_hi:[1,0]
	v_pk_mul_f32 v[120:121], v[120:121], v[160:161] op_sel_hi:[1,0]
	v_pk_mul_f32 v[118:119], v[118:119], v[160:161] op_sel_hi:[1,0]
	v_pk_mul_f32 v[116:117], v[116:117], v[160:161] op_sel_hi:[1,0]
	v_pk_mul_f32 v[114:115], v[114:115], v[160:161] op_sel_hi:[1,0]
	v_pk_mul_f32 v[112:113], v[112:113], v[160:161] op_sel_hi:[1,0]
	v_max_f32_e32 v124, 0, v124
	v_max_f32_e32 v120, 0, v120
	v_max_f32_e32 v125, 0, v125
	v_max_f32_e32 v121, 0, v121
	v_max_f32_e32 v126, 0, v126
	v_max_f32_e32 v122, 0, v122
	v_max_f32_e32 v127, 0, v127
	v_max_f32_e32 v123, 0, v123
	v_max_f32_e32 v116, 0, v116
	v_max_f32_e32 v112, 0, v112
	v_max_f32_e32 v117, 0, v117
	v_max_f32_e32 v113, 0, v113
	v_max_f32_e32 v118, 0, v118
	v_max_f32_e32 v114, 0, v114
	v_max_f32_e32 v119, 0, v119
	v_max_f32_e32 v115, 0, v115
	v_pk_mul_f32 v[124:125], v[124:125], v[124:125]
	v_pk_mul_f32 v[120:121], v[120:121], v[120:121]
	v_pk_mul_f32 v[126:127], v[126:127], v[126:127]
	v_pk_mul_f32 v[122:123], v[122:123], v[122:123]
	v_pk_mul_f32 v[116:117], v[116:117], v[116:117]
	v_pk_mul_f32 v[160:161], v[112:113], v[112:113]
	v_pk_mul_f32 v[118:119], v[118:119], v[118:119]
	v_pk_mul_f32 v[162:163], v[114:115], v[114:115]
	v_cvt_pk_bf16_f32 v112, v124, v125
	v_cvt_pk_bf16_f32 v113, v126, v127
	v_cvt_pk_bf16_f32 v114, v120, v121
	v_cvt_pk_bf16_f32 v115, v122, v123
	v_cvt_pk_bf16_f32 v116, v116, v117
	v_cvt_pk_bf16_f32 v117, v118, v119
	v_cvt_pk_bf16_f32 v118, v160, v161
	v_cvt_pk_bf16_f32 v119, v162, v163
	global_store_dwordx4 v[142:143], v[112:115], off
	global_store_dwordx4 v[142:143], v[116:119], off offset:256
	global_load_dword v114, v[144:145], off offset:64
	v_or_b32_e32 v112, 16, v146
	v_ashrrev_i32_e32 v113, 31, v112
	v_lshlrev_b64 v[112:113], 13, v[112:113]
	v_lshl_add_u64 v[112:113], s[48:49], 0, v[112:113]
	v_lshl_add_u64 v[112:113], v[112:113], 0, s[14:15]
	v_lshl_add_u64 v[112:113], v[112:113], 0, v[132:133]
	s_waitcnt vmcnt(0)
	v_fmamk_f32 v114, v114, 0x3a800000, v148
	v_rsq_f32_e32 v114, v114
	s_nop 0
	v_pk_mul_f32 v[110:111], v[110:111], v[114:115] op_sel_hi:[1,0]
	v_pk_mul_f32 v[108:109], v[108:109], v[114:115] op_sel_hi:[1,0]
	v_pk_mul_f32 v[106:107], v[106:107], v[114:115] op_sel_hi:[1,0]
	v_pk_mul_f32 v[104:105], v[104:105], v[114:115] op_sel_hi:[1,0]
	v_pk_mul_f32 v[102:103], v[102:103], v[114:115] op_sel_hi:[1,0]
	v_pk_mul_f32 v[100:101], v[100:101], v[114:115] op_sel_hi:[1,0]
	v_pk_mul_f32 v[98:99], v[98:99], v[114:115] op_sel_hi:[1,0]
	v_pk_mul_f32 v[96:97], v[96:97], v[114:115] op_sel_hi:[1,0]
	v_max_f32_e32 v108, 0, v108
	v_max_f32_e32 v104, 0, v104
	v_max_f32_e32 v109, 0, v109
	v_max_f32_e32 v105, 0, v105
	v_max_f32_e32 v110, 0, v110
	v_max_f32_e32 v106, 0, v106
	v_max_f32_e32 v111, 0, v111
	v_max_f32_e32 v107, 0, v107
	v_max_f32_e32 v100, 0, v100
	v_max_f32_e32 v96, 0, v96
	v_max_f32_e32 v101, 0, v101
	v_max_f32_e32 v97, 0, v97
	v_max_f32_e32 v102, 0, v102
	v_max_f32_e32 v98, 0, v98
	v_max_f32_e32 v103, 0, v103
	v_max_f32_e32 v99, 0, v99
	v_pk_mul_f32 v[108:109], v[108:109], v[108:109]
	v_pk_mul_f32 v[104:105], v[104:105], v[104:105]
	v_pk_mul_f32 v[110:111], v[110:111], v[110:111]
	v_pk_mul_f32 v[106:107], v[106:107], v[106:107]
	v_pk_mul_f32 v[100:101], v[100:101], v[100:101]
	v_pk_mul_f32 v[114:115], v[96:97], v[96:97]
	v_pk_mul_f32 v[102:103], v[102:103], v[102:103]
	v_pk_mul_f32 v[116:117], v[98:99], v[98:99]
	v_cvt_pk_bf16_f32 v96, v108, v109
	v_cvt_pk_bf16_f32 v97, v110, v111
	v_cvt_pk_bf16_f32 v98, v104, v105
	v_cvt_pk_bf16_f32 v99, v106, v107
	v_cvt_pk_bf16_f32 v100, v100, v101
	v_cvt_pk_bf16_f32 v101, v102, v103
	v_cvt_pk_bf16_f32 v102, v114, v115
	v_cvt_pk_bf16_f32 v103, v116, v117
	global_store_dwordx4 v[112:113], v[96:99], off
	global_store_dwordx4 v[112:113], v[100:103], off offset:256
	global_load_dword v98, v[144:145], off offset:128
	v_or_b32_e32 v96, 32, v146
	v_ashrrev_i32_e32 v97, 31, v96
	v_lshlrev_b64 v[96:97], 13, v[96:97]
	v_lshl_add_u64 v[96:97], s[48:49], 0, v[96:97]
	v_lshl_add_u64 v[96:97], v[96:97], 0, s[14:15]
	v_lshl_add_u64 v[96:97], v[96:97], 0, v[132:133]
	s_waitcnt vmcnt(0)
	v_fmamk_f32 v98, v98, 0x3a800000, v148
	v_rsq_f32_e32 v98, v98
	s_nop 0
	v_pk_mul_f32 v[94:95], v[94:95], v[98:99] op_sel_hi:[1,0]
	v_pk_mul_f32 v[92:93], v[92:93], v[98:99] op_sel_hi:[1,0]
	v_pk_mul_f32 v[90:91], v[90:91], v[98:99] op_sel_hi:[1,0]
	v_pk_mul_f32 v[88:89], v[88:89], v[98:99] op_sel_hi:[1,0]
	v_pk_mul_f32 v[86:87], v[86:87], v[98:99] op_sel_hi:[1,0]
	v_pk_mul_f32 v[84:85], v[84:85], v[98:99] op_sel_hi:[1,0]
	v_pk_mul_f32 v[82:83], v[82:83], v[98:99] op_sel_hi:[1,0]
	v_pk_mul_f32 v[80:81], v[80:81], v[98:99] op_sel_hi:[1,0]
	v_max_f32_e32 v92, 0, v92
	v_max_f32_e32 v88, 0, v88
	v_max_f32_e32 v93, 0, v93
	v_max_f32_e32 v89, 0, v89
	v_max_f32_e32 v94, 0, v94
	v_max_f32_e32 v90, 0, v90
	v_max_f32_e32 v95, 0, v95
	v_max_f32_e32 v91, 0, v91
	v_max_f32_e32 v84, 0, v84
	v_max_f32_e32 v80, 0, v80
	v_max_f32_e32 v85, 0, v85
	v_max_f32_e32 v81, 0, v81
	v_max_f32_e32 v86, 0, v86
	v_max_f32_e32 v82, 0, v82
	v_max_f32_e32 v87, 0, v87
	v_max_f32_e32 v83, 0, v83
	v_pk_mul_f32 v[92:93], v[92:93], v[92:93]
	v_pk_mul_f32 v[88:89], v[88:89], v[88:89]
	v_pk_mul_f32 v[94:95], v[94:95], v[94:95]
	v_pk_mul_f32 v[90:91], v[90:91], v[90:91]
	v_pk_mul_f32 v[84:85], v[84:85], v[84:85]
	v_pk_mul_f32 v[98:99], v[80:81], v[80:81]
	v_pk_mul_f32 v[86:87], v[86:87], v[86:87]
	v_pk_mul_f32 v[100:101], v[82:83], v[82:83]
	v_cvt_pk_bf16_f32 v80, v92, v93
	v_cvt_pk_bf16_f32 v81, v94, v95
	v_cvt_pk_bf16_f32 v82, v88, v89
	v_cvt_pk_bf16_f32 v83, v90, v91
	v_cvt_pk_bf16_f32 v84, v84, v85
	v_cvt_pk_bf16_f32 v85, v86, v87
	v_cvt_pk_bf16_f32 v86, v98, v99
	v_cvt_pk_bf16_f32 v87, v100, v101
	global_store_dwordx4 v[96:97], v[80:83], off
	global_store_dwordx4 v[96:97], v[84:87], off offset:256
	global_load_dword v82, v[144:145], off offset:192
	v_or_b32_e32 v80, 48, v146
	v_ashrrev_i32_e32 v81, 31, v80
	v_lshlrev_b64 v[80:81], 13, v[80:81]
	v_lshl_add_u64 v[80:81], s[48:49], 0, v[80:81]
	v_lshl_add_u64 v[80:81], v[80:81], 0, s[14:15]
	v_lshl_add_u64 v[80:81], v[80:81], 0, v[132:133]
	s_mov_b64 s[14:15], 0x100000
	s_waitcnt vmcnt(0)
	v_fmamk_f32 v82, v82, 0x3a800000, v148
	v_rsq_f32_e32 v82, v82
	s_nop 0
	v_pk_mul_f32 v[78:79], v[78:79], v[82:83] op_sel_hi:[1,0]
	v_pk_mul_f32 v[76:77], v[76:77], v[82:83] op_sel_hi:[1,0]
	v_pk_mul_f32 v[74:75], v[74:75], v[82:83] op_sel_hi:[1,0]
	v_pk_mul_f32 v[72:73], v[72:73], v[82:83] op_sel_hi:[1,0]
	v_pk_mul_f32 v[70:71], v[70:71], v[82:83] op_sel_hi:[1,0]
	v_pk_mul_f32 v[68:69], v[68:69], v[82:83] op_sel_hi:[1,0]
	v_pk_mul_f32 v[66:67], v[66:67], v[82:83] op_sel_hi:[1,0]
	v_pk_mul_f32 v[64:65], v[64:65], v[82:83] op_sel_hi:[1,0]
	v_max_f32_e32 v76, 0, v76
	v_max_f32_e32 v72, 0, v72
	v_max_f32_e32 v77, 0, v77
	v_max_f32_e32 v73, 0, v73
	v_max_f32_e32 v78, 0, v78
	v_max_f32_e32 v74, 0, v74
	v_max_f32_e32 v79, 0, v79
	v_max_f32_e32 v75, 0, v75
	v_max_f32_e32 v68, 0, v68
	v_max_f32_e32 v64, 0, v64
	v_max_f32_e32 v69, 0, v69
	v_max_f32_e32 v65, 0, v65
	v_max_f32_e32 v70, 0, v70
	v_max_f32_e32 v66, 0, v66
	v_max_f32_e32 v71, 0, v71
	v_max_f32_e32 v67, 0, v67
	v_pk_mul_f32 v[76:77], v[76:77], v[76:77]
	v_pk_mul_f32 v[72:73], v[72:73], v[72:73]
	v_pk_mul_f32 v[78:79], v[78:79], v[78:79]
	v_pk_mul_f32 v[74:75], v[74:75], v[74:75]
	v_pk_mul_f32 v[68:69], v[68:69], v[68:69]
	v_pk_mul_f32 v[82:83], v[64:65], v[64:65]
	v_pk_mul_f32 v[70:71], v[70:71], v[70:71]
	v_pk_mul_f32 v[84:85], v[66:67], v[66:67]
	v_cvt_pk_bf16_f32 v64, v76, v77
	v_cvt_pk_bf16_f32 v65, v78, v79
	v_cvt_pk_bf16_f32 v66, v72, v73
	v_cvt_pk_bf16_f32 v67, v74, v75
	v_cvt_pk_bf16_f32 v68, v68, v69
	v_cvt_pk_bf16_f32 v69, v70, v71
	v_cvt_pk_bf16_f32 v70, v82, v83
	v_cvt_pk_bf16_f32 v71, v84, v85
	global_store_dwordx4 v[80:81], v[64:67], off
	global_store_dwordx4 v[80:81], v[68:71], off offset:256
	global_load_dword v66, v[144:145], off offset:512
	v_lshl_add_u64 v[64:65], v[142:143], 0, s[14:15]
	v_add_co_u32_e32 v68, vcc, s11, v142
	s_mov_b32 s11, 0x120000
	s_nop 0
	v_addc_co_u32_e32 v69, vcc, 0, v143, vcc
	s_mov_b64 s[14:15], 0x120000
	s_waitcnt vmcnt(0)
	v_fmamk_f32 v66, v66, 0x3a800000, v148
	v_rsq_f32_e32 v66, v66
	s_nop 0
	v_pk_mul_f32 v[62:63], v[62:63], v[66:67] op_sel_hi:[1,0]
	v_pk_mul_f32 v[60:61], v[60:61], v[66:67] op_sel_hi:[1,0]
	v_pk_mul_f32 v[58:59], v[58:59], v[66:67] op_sel_hi:[1,0]
	v_pk_mul_f32 v[56:57], v[56:57], v[66:67] op_sel_hi:[1,0]
	v_pk_mul_f32 v[54:55], v[54:55], v[66:67] op_sel_hi:[1,0]
	v_pk_mul_f32 v[52:53], v[52:53], v[66:67] op_sel_hi:[1,0]
	v_pk_mul_f32 v[50:51], v[50:51], v[66:67] op_sel_hi:[1,0]
	v_pk_mul_f32 v[48:49], v[48:49], v[66:67] op_sel_hi:[1,0]
	v_max_f32_e32 v60, 0, v60
	v_max_f32_e32 v56, 0, v56
	v_max_f32_e32 v61, 0, v61
	v_max_f32_e32 v57, 0, v57
	v_max_f32_e32 v62, 0, v62
	v_max_f32_e32 v58, 0, v58
	v_max_f32_e32 v63, 0, v63
	v_max_f32_e32 v59, 0, v59
	v_max_f32_e32 v52, 0, v52
	v_max_f32_e32 v48, 0, v48
	v_max_f32_e32 v53, 0, v53
	v_max_f32_e32 v49, 0, v49
	v_max_f32_e32 v54, 0, v54
	v_max_f32_e32 v50, 0, v50
	v_max_f32_e32 v55, 0, v55
	v_max_f32_e32 v51, 0, v51
	v_pk_mul_f32 v[60:61], v[60:61], v[60:61]
	v_pk_mul_f32 v[56:57], v[56:57], v[56:57]
	v_pk_mul_f32 v[62:63], v[62:63], v[62:63]
	v_pk_mul_f32 v[58:59], v[58:59], v[58:59]
	v_pk_mul_f32 v[52:53], v[52:53], v[52:53]
	v_pk_mul_f32 v[66:67], v[48:49], v[48:49]
	v_pk_mul_f32 v[54:55], v[54:55], v[54:55]
	v_pk_mul_f32 v[70:71], v[50:51], v[50:51]
	v_cvt_pk_bf16_f32 v48, v60, v61
	v_cvt_pk_bf16_f32 v49, v62, v63
	v_cvt_pk_bf16_f32 v50, v56, v57
	v_cvt_pk_bf16_f32 v51, v58, v59
	v_cvt_pk_bf16_f32 v52, v52, v53
	v_cvt_pk_bf16_f32 v53, v54, v55
	v_cvt_pk_bf16_f32 v54, v66, v67
	v_cvt_pk_bf16_f32 v55, v70, v71
	global_store_dwordx4 v[68:69], v[48:51], off
	global_store_dwordx4 v[64:65], v[52:55], off offset:256
	global_load_dword v50, v[144:145], off offset:576
	v_lshl_add_u64 v[48:49], v[142:143], 0, s[14:15]
	v_add_co_u32_e32 v52, vcc, s11, v142
	s_mov_b32 s11, 0x140000
	s_nop 0
	v_addc_co_u32_e32 v53, vcc, 0, v143, vcc
	s_mov_b64 s[14:15], 0x140000
	s_waitcnt vmcnt(0)
	v_fmamk_f32 v50, v50, 0x3a800000, v148
	v_rsq_f32_e32 v50, v50
	s_nop 0
	v_pk_mul_f32 v[46:47], v[46:47], v[50:51] op_sel_hi:[1,0]
	v_pk_mul_f32 v[44:45], v[44:45], v[50:51] op_sel_hi:[1,0]
	v_pk_mul_f32 v[42:43], v[42:43], v[50:51] op_sel_hi:[1,0]
	v_pk_mul_f32 v[40:41], v[40:41], v[50:51] op_sel_hi:[1,0]
	v_pk_mul_f32 v[38:39], v[38:39], v[50:51] op_sel_hi:[1,0]
	v_pk_mul_f32 v[36:37], v[36:37], v[50:51] op_sel_hi:[1,0]
	v_pk_mul_f32 v[34:35], v[34:35], v[50:51] op_sel_hi:[1,0]
	v_pk_mul_f32 v[32:33], v[32:33], v[50:51] op_sel_hi:[1,0]
	v_max_f32_e32 v44, 0, v44
	v_max_f32_e32 v40, 0, v40
	v_max_f32_e32 v45, 0, v45
	v_max_f32_e32 v41, 0, v41
	v_max_f32_e32 v46, 0, v46
	v_max_f32_e32 v42, 0, v42
	v_max_f32_e32 v47, 0, v47
	v_max_f32_e32 v43, 0, v43
	v_max_f32_e32 v36, 0, v36
	v_max_f32_e32 v32, 0, v32
	v_max_f32_e32 v37, 0, v37
	v_max_f32_e32 v33, 0, v33
	v_max_f32_e32 v38, 0, v38
	v_max_f32_e32 v34, 0, v34
	v_max_f32_e32 v39, 0, v39
	v_max_f32_e32 v35, 0, v35
	v_pk_mul_f32 v[44:45], v[44:45], v[44:45]
	v_pk_mul_f32 v[40:41], v[40:41], v[40:41]
	v_pk_mul_f32 v[46:47], v[46:47], v[46:47]
	v_pk_mul_f32 v[42:43], v[42:43], v[42:43]
	v_pk_mul_f32 v[36:37], v[36:37], v[36:37]
	v_pk_mul_f32 v[50:51], v[32:33], v[32:33]
	v_pk_mul_f32 v[38:39], v[38:39], v[38:39]
	v_pk_mul_f32 v[54:55], v[34:35], v[34:35]
	v_cvt_pk_bf16_f32 v32, v44, v45
	v_cvt_pk_bf16_f32 v33, v46, v47
	v_cvt_pk_bf16_f32 v34, v40, v41
	v_cvt_pk_bf16_f32 v35, v42, v43
	v_cvt_pk_bf16_f32 v36, v36, v37
	v_cvt_pk_bf16_f32 v37, v38, v39
	v_cvt_pk_bf16_f32 v38, v50, v51
	v_cvt_pk_bf16_f32 v39, v54, v55
	global_store_dwordx4 v[52:53], v[32:35], off
	global_store_dwordx4 v[48:49], v[36:39], off offset:256
	global_load_dword v34, v[144:145], off offset:640
	v_lshl_add_u64 v[32:33], v[142:143], 0, s[14:15]
	v_add_co_u32_e32 v36, vcc, s11, v142
	s_mov_b32 s11, 0x160000
	s_nop 0
	v_addc_co_u32_e32 v37, vcc, 0, v143, vcc
	s_andn2_b64 vcc, exec, s[36:37]
	s_mov_b64 s[14:15], 0x160000
	s_waitcnt vmcnt(0)
	v_fmamk_f32 v34, v34, 0x3a800000, v148
	v_rsq_f32_e32 v34, v34
	s_nop 0
	v_pk_mul_f32 v[30:31], v[30:31], v[34:35] op_sel_hi:[1,0]
	v_pk_mul_f32 v[28:29], v[28:29], v[34:35] op_sel_hi:[1,0]
	v_pk_mul_f32 v[26:27], v[26:27], v[34:35] op_sel_hi:[1,0]
	v_pk_mul_f32 v[24:25], v[24:25], v[34:35] op_sel_hi:[1,0]
	v_pk_mul_f32 v[22:23], v[22:23], v[34:35] op_sel_hi:[1,0]
	v_pk_mul_f32 v[20:21], v[20:21], v[34:35] op_sel_hi:[1,0]
	v_pk_mul_f32 v[18:19], v[18:19], v[34:35] op_sel_hi:[1,0]
	v_pk_mul_f32 v[16:17], v[16:17], v[34:35] op_sel_hi:[1,0]
	v_max_f32_e32 v28, 0, v28
	v_max_f32_e32 v24, 0, v24
	v_max_f32_e32 v29, 0, v29
	v_max_f32_e32 v25, 0, v25
	v_max_f32_e32 v30, 0, v30
	v_max_f32_e32 v26, 0, v26
	v_max_f32_e32 v31, 0, v31
	v_max_f32_e32 v27, 0, v27
	v_max_f32_e32 v20, 0, v20
	v_max_f32_e32 v16, 0, v16
	v_max_f32_e32 v21, 0, v21
	v_max_f32_e32 v17, 0, v17
	v_max_f32_e32 v22, 0, v22
	v_max_f32_e32 v18, 0, v18
	v_max_f32_e32 v23, 0, v23
	v_max_f32_e32 v19, 0, v19
	v_pk_mul_f32 v[28:29], v[28:29], v[28:29]
	v_pk_mul_f32 v[24:25], v[24:25], v[24:25]
	v_pk_mul_f32 v[30:31], v[30:31], v[30:31]
	v_pk_mul_f32 v[26:27], v[26:27], v[26:27]
	v_pk_mul_f32 v[20:21], v[20:21], v[20:21]
	v_pk_mul_f32 v[34:35], v[16:17], v[16:17]
	v_pk_mul_f32 v[22:23], v[22:23], v[22:23]
	v_pk_mul_f32 v[38:39], v[18:19], v[18:19]
	v_cvt_pk_bf16_f32 v16, v28, v29
	v_cvt_pk_bf16_f32 v17, v30, v31
	v_cvt_pk_bf16_f32 v18, v24, v25
	v_cvt_pk_bf16_f32 v19, v26, v27
	v_cvt_pk_bf16_f32 v20, v20, v21
	v_cvt_pk_bf16_f32 v21, v22, v23
	v_cvt_pk_bf16_f32 v22, v34, v35
	v_cvt_pk_bf16_f32 v23, v38, v39
	global_store_dwordx4 v[36:37], v[16:19], off
	global_store_dwordx4 v[32:33], v[20:23], off offset:256
	global_load_dword v18, v[144:145], off offset:704
	v_lshl_add_u64 v[16:17], v[142:143], 0, s[14:15]
	v_add_co_u32_e64 v20, s[36:37], s11, v142
	s_mov_b64 s[14:15], -1
	s_nop 0
	v_addc_co_u32_e64 v21, s[36:37], 0, v143, s[36:37]
	s_waitcnt vmcnt(0)
	v_fmamk_f32 v18, v18, 0x3a800000, v148
	v_rsq_f32_e32 v18, v18
	s_nop 0
	v_pk_mul_f32 v[14:15], v[14:15], v[18:19] op_sel_hi:[1,0]
	v_pk_mul_f32 v[12:13], v[12:13], v[18:19] op_sel_hi:[1,0]
	v_pk_mul_f32 v[10:11], v[10:11], v[18:19] op_sel_hi:[1,0]
	v_pk_mul_f32 v[8:9], v[8:9], v[18:19] op_sel_hi:[1,0]
	v_pk_mul_f32 v[6:7], v[6:7], v[18:19] op_sel_hi:[1,0]
	v_pk_mul_f32 v[4:5], v[4:5], v[18:19] op_sel_hi:[1,0]
	v_pk_mul_f32 v[2:3], v[2:3], v[18:19] op_sel_hi:[1,0]
	v_pk_mul_f32 v[0:1], v[0:1], v[18:19] op_sel_hi:[1,0]
	v_max_f32_e32 v12, 0, v12
	v_max_f32_e32 v8, 0, v8
	v_max_f32_e32 v13, 0, v13
	v_max_f32_e32 v9, 0, v9
	v_max_f32_e32 v14, 0, v14
	v_max_f32_e32 v10, 0, v10
	v_max_f32_e32 v15, 0, v15
	v_max_f32_e32 v11, 0, v11
	v_max_f32_e32 v4, 0, v4
	v_max_f32_e32 v0, 0, v0
	v_max_f32_e32 v5, 0, v5
	v_max_f32_e32 v1, 0, v1
	v_max_f32_e32 v6, 0, v6
	v_max_f32_e32 v2, 0, v2
	v_max_f32_e32 v7, 0, v7
	v_max_f32_e32 v3, 0, v3
	v_pk_mul_f32 v[12:13], v[12:13], v[12:13]
	v_pk_mul_f32 v[8:9], v[8:9], v[8:9]
	v_pk_mul_f32 v[14:15], v[14:15], v[14:15]
	v_pk_mul_f32 v[10:11], v[10:11], v[10:11]
	v_pk_mul_f32 v[4:5], v[4:5], v[4:5]
	v_pk_mul_f32 v[18:19], v[0:1], v[0:1]
	v_pk_mul_f32 v[6:7], v[6:7], v[6:7]
	v_pk_mul_f32 v[22:23], v[2:3], v[2:3]
	v_cvt_pk_bf16_f32 v0, v12, v13
	v_cvt_pk_bf16_f32 v1, v14, v15
	v_cvt_pk_bf16_f32 v2, v8, v9
	v_cvt_pk_bf16_f32 v3, v10, v11
	v_cvt_pk_bf16_f32 v4, v4, v5
	v_cvt_pk_bf16_f32 v5, v6, v7
	v_cvt_pk_bf16_f32 v6, v18, v19
	v_cvt_pk_bf16_f32 v7, v22, v23
	global_store_dwordx4 v[20:21], v[0:3], off
	global_store_dwordx4 v[16:17], v[4:7], off offset:256
	s_barrier
	s_cbranch_vccnz .LBB0_656
	s_andn2_b64 vcc, exec, s[4:5]
	s_cbranch_vccnz .LBB0_655
	s_barrier
	s_branch .LBB0_655
